# S5 pass 1 and pass 2 item preambles: pointers by scalar loads, all parameter, B-matrix and u-fragment loads issued together at the top (one round trip instead of up to three)
# baseline (speedup 1.0000x reference)
; __device__ __forceinline__ int tid_fresh() { int t = threadIdx.x; asm volatile("" : "+v"(t)); return t; }
; __device__ __forceinline__ void s5_lane_params(PP p, int l, int g, int n, S5Lane& q) {
;     const int gi = (l * 32 + g) * 64 + n;
;     const float lr = p->in[6][gi], li = p->in[7][gi], dt = expf(p->in[8][l * 32 + g]);
;     const float mag = expf(lr * dt);
;     float sn, cs; sincosf(li * dt, &sn, &cs);
;     q.ar = mag * cs; q.ai = mag * sn;
;     const float den = lr * lr + li * li, nr = q.ar - 1.0f, ni = q.ai;
;     const float fr_ = (nr * lr + ni * li) / den, fi_ = (ni * lr - nr * li) / den;
;     const f32x4* bre = (const f32x4*)(p->in[9] + (size_t)gi * 16); const f32x4* bim = (const f32x4*)(p->in[10] + (size_t)gi * 16);
; __device__ __forceinline__ void s5_pass1_item(PP p, unsigned char* shm, int item, int l) {
;     const int tid = tid_fresh(), w = tid >> 6, lane = tid & 63;
;     const int b = item / 128, g = (item / 4) % 32, jg = item % 4, j = jg * 8 + w;
;     const bf16_t* proj = (const bf16_t*)(p->ws + WS_PROJ);
;     bf16_t* bbL = (bf16_t*)(shm + S5_BBL); float* buL = (float*)(shm + S5_BUL) + w * 2048;
;     S5Lane q; s5_lane_params(p, l, g, lane, q);
;     const size_t row0 = (size_t)b * SEQ + j * 64;
;     bf16x8 uf[4];
; #pragma unroll
;     for (int sc = 0; sc < 4; ++sc) uf[sc] = s5_ufrag(proj, row0 + sc * 16, g, lane);
.LBB0_604:
	s_add_i32 s18, s14, 0xfffffa00
	s_ashr_i32 s21, s18, 31
	s_lshr_b32 s2, s21, 30
	s_add_i32 s2, s18, s2
	s_ashr_i32 s20, s2, 2
	s_ashr_i32 s2, s2, 31
	s_lshr_b32 s2, s2, 27
	v_mov_b32_e32 v4, v222
	s_add_i32 s2, s20, s2
	s_and_b32 s9, s2, 0xffffffe0
	s_load_dwordx2 s[2:3], s[28:29], 0x40
	s_load_dwordx4 s[36:39], s[28:29], 0x30
	s_load_dwordx4 s[40:43], s[28:29], 0x48
	s_load_dwordx2 s[34:35], s[28:29], 0x110
	s_sub_i32 s9, s20, s9
	s_add_i32 s12, s9, s54
	s_ashr_i32 s13, s12, 31
	s_lshl_b64 s[22:23], s[12:13], 2
	s_waitcnt lgkmcnt(0)
	s_add_u32 s2, s2, s22
	s_addc_u32 s3, s3, s23
	global_load_dword v0, v1, s[2:3]
	v_and_b32_e32 v55, 63, v4
	v_lshl_or_b32 v2, s12, 6, v55
	v_ashrrev_i32_e32 v3, 31, v2
	v_lshlrev_b64 v[6:7], 2, v[2:3]
	v_lshl_add_u64 v[8:9], s[38:39], 0, v[6:7]
	global_load_dword v51, v[8:9], off
	v_lshl_add_u64 v[6:7], s[36:37], 0, v[6:7]
	global_load_dword v50, v[6:7], off
	v_lshlrev_b64 v[212:213], 6, v[2:3]
	v_lshl_add_u64 v[214:215], s[40:41], 0, v[212:213]
	v_lshl_add_u64 v[212:213], s[42:43], 0, v[212:213]
	global_load_dwordx4 v[130:133], v[214:215], off offset:48
	global_load_dwordx4 v[134:137], v[214:215], off offset:32
	global_load_dwordx4 v[138:141], v[214:215], off offset:16
	global_load_dwordx4 v[142:145], v[214:215], off
	global_load_dwordx4 v[146:149], v[212:213], off offset:48
	global_load_dwordx4 v[150:153], v[212:213], off offset:32
	global_load_dwordx4 v[154:157], v[212:213], off offset:16
	global_load_dwordx4 v[158:161], v[212:213], off
	s_lshr_b32 s22, s21, 25
	s_add_i32 s22, s18, s22
	s_ashr_i32 s22, s22, 7
	s_ashr_i32 s23, s22, 31
	s_lshl_b64 s[22:23], s[22:23], 11
	s_lshl_b32 s98, s20, 2
	s_sub_i32 s98, s18, s98
	v_ashrrev_i32_e32 v216, 6, v4
	v_lshl_add_u32 v216, s98, 3, v216
	v_lshlrev_b32_e32 v216, 6, v216
	v_ashrrev_i32_e32 v217, 31, v216
	v_lshl_add_u64 v[216:217], s[22:23], 0, v[216:217]
	v_and_or_b32 v216, v4, 15, v216
	v_lshlrev_b64 v[216:217], 10, v[216:217]
	s_lshl_b32 s22, s9, 4
	s_ashr_i32 s23, s22, 31
	s_lshl_b64 s[22:23], s[22:23], 1
	s_add_u32 s22, s34, s22
	s_addc_u32 s23, s35, s23
	s_add_u32 s22, s22, 0x1de00000
	s_addc_u32 s23, s23, 0
	v_lshrrev_b32_e32 v218, 1, v4
	v_and_b32_e32 v218, 8, v218
	v_lshlrev_b32_e32 v218, 1, v218
	v_mov_b32_e32 v219, 0
	v_lshl_add_u64 v[218:219], s[22:23], 0, v[218:219]
	v_lshl_add_u64 v[216:217], v[218:219], 0, v[216:217]
	v_mov_b32_e32 v162, 0
	v_mov_b32_e32 v163, 0
	v_mov_b32_e32 v164, 0
	v_mov_b32_e32 v165, 0
	v_mov_b32_e32 v166, 0
	v_mov_b32_e32 v167, 0
	v_mov_b32_e32 v168, 0
	v_mov_b32_e32 v169, 0
	v_mov_b32_e32 v170, 0
	v_mov_b32_e32 v171, 0
	v_mov_b32_e32 v172, 0
	v_mov_b32_e32 v173, 0
	v_mov_b32_e32 v174, 0
	v_mov_b32_e32 v175, 0
	v_mov_b32_e32 v176, 0
	v_mov_b32_e32 v177, 0
	v_cmp_gt_u32_e32 vcc, 32, v55
	s_and_saveexec_b64 s[22:23], vcc
	global_load_dwordx4 v[162:165], v[216:217], off
	v_add_co_u32_e32 v218, vcc, 0x4000, v216
	s_nop 1
	v_addc_co_u32_e32 v219, vcc, 0, v217, vcc
	global_load_dwordx4 v[166:169], v[218:219], off
	v_add_co_u32_e32 v218, vcc, 0x8000, v216
	s_nop 1
	v_addc_co_u32_e32 v219, vcc, 0, v217, vcc
	global_load_dwordx4 v[170:173], v[218:219], off
	v_add_co_u32_e32 v218, vcc, 0xc000, v216
	s_nop 1
	v_addc_co_u32_e32 v219, vcc, 0, v217, vcc
	global_load_dwordx4 v[174:177], v[218:219], off
	s_or_b64 exec, exec, s[22:23]
	s_mov_b32 s2, 0x3fb8aa3b
	s_waitcnt vmcnt(14)
	v_mul_f32_e32 v5, 0x3fb8aa3b, v0
	v_fma_f32 v6, v0, s2, -v5
	v_rndne_f32_e32 v7, v5
	v_fmac_f32_e32 v6, 0x32a5705f, v0
	v_sub_f32_e32 v5, v5, v7
	v_add_f32_e32 v5, v5, v6
	v_cvt_i32_f32_e32 v7, v7
	v_exp_f32_e32 v5, v5
	s_mov_b32 s2, 0xc2ce8ed0
	v_cmp_ngt_f32_e32 vcc, s2, v0
	s_mov_b32 s2, 0x42b17218
	v_ldexp_f32 v5, v5, v7
	v_cndmask_b32_e32 v5, 0, v5, vcc
	v_cmp_nlt_f32_e32 vcc, s2, v0
	s_brev_b32 s2, 18
	s_nop 0
	v_cndmask_b32_e32 v59, v231, v5, vcc
	s_waitcnt vmcnt(13)
	v_mul_f32_e32 v57, v51, v59
	v_and_b32_e32 v58, 0x7fffffff, v57
	v_cmp_nlt_f32_e64 s[2:3], |v57|, s2
	s_and_saveexec_b64 s[12:13], s[2:3]
	s_xor_b64 s[2:3], exec, s[12:13]
	s_cbranch_execz .LBB0_606
; __device__ __forceinline__ void s5_lane_params(PP p, int l, int g, int n, S5Lane& q) {
;     ...
;     const float lr = p->in[6][gi], li = p->in[7][gi], dt = expf(p->in[8][l * 32 + g]);
;     const float mag = expf(lr * dt);
;     float sn, cs; sincosf(li * dt, &sn, &cs);
;     q.ar = mag * cs; q.ai = mag * sn;
	v_lshrrev_b32_e32 v0, 23, v58
	v_add_u32_e32 v0, 0xffffff88, v0
	v_cmp_lt_u32_e32 vcc, 63, v0
	v_not_b32_e32 v5, 63
	v_not_b32_e32 v6, 31
	v_cndmask_b32_e32 v5, 0, v5, vcc
	v_add_u32_e32 v0, v5, v0
	v_cmp_lt_u32_e64 s[38:39], 31, v0
	s_mov_b32 s12, 0xfe5163ab
	s_nop 0
	v_cndmask_b32_e64 v5, 0, v6, s[38:39]
	v_add_u32_e32 v0, v5, v0
	v_cmp_lt_u32_e64 s[40:41], 31, v0
	s_nop 1
	v_cndmask_b32_e64 v5, 0, v6, s[40:41]
	v_add_u32_e32 v5, v5, v0
	v_and_b32_e32 v0, 0x7fffff, v58
	v_or_b32_e32 v18, 0x800000, v0
	v_mad_u64_u32 v[6:7], s[12:13], v18, s12, 0
	v_mov_b32_e32 v0, v7
	s_mov_b32 s12, 0x3c439041
	v_mad_u64_u32 v[8:9], s[12:13], v18, s12, v[0:1]
	v_mov_b32_e32 v0, v9
	s_mov_b32 s12, 0xdb629599
	v_mad_u64_u32 v[10:11], s[12:13], v18, s12, v[0:1]
	v_mov_b32_e32 v0, v11
	s_mov_b32 s12, 0xf534ddc0
	v_mad_u64_u32 v[12:13], s[12:13], v18, s12, v[0:1]
	v_mov_b32_e32 v0, v13
	s_mov_b32 s12, 0xfc2757d1
	v_mad_u64_u32 v[14:15], s[12:13], v18, s12, v[0:1]
	v_mov_b32_e32 v0, v15
	s_mov_b32 s12, 0x4e441529
	v_mad_u64_u32 v[16:17], s[12:13], v18, s12, v[0:1]
	v_mov_b32_e32 v0, v17
	s_mov_b32 s12, 0xa2f9836e
	v_mad_u64_u32 v[18:19], s[12:13], v18, s12, v[0:1]
	v_cndmask_b32_e32 v7, v16, v12, vcc
	v_cndmask_b32_e32 v0, v18, v14, vcc
	v_cndmask_b32_e32 v11, v19, v16, vcc
	v_cndmask_b32_e64 v9, v0, v7, s[38:39]
	v_cndmask_b32_e64 v0, v11, v0, s[38:39]
	v_cndmask_b32_e32 v11, v14, v10, vcc
	v_cndmask_b32_e64 v7, v7, v11, s[38:39]
	v_sub_u32_e32 v13, 32, v5
	v_cmp_eq_u32_e64 s[42:43], 0, v5
	v_cndmask_b32_e32 v5, v12, v8, vcc
	v_cndmask_b32_e64 v0, v0, v9, s[40:41]
	v_cndmask_b32_e64 v9, v9, v7, s[40:41]
	v_cndmask_b32_e64 v8, v11, v5, s[38:39]
	v_alignbit_b32 v14, v0, v9, v13
	v_cndmask_b32_e64 v7, v7, v8, s[40:41]
	v_cndmask_b32_e64 v0, v14, v0, s[42:43]
	v_alignbit_b32 v11, v9, v7, v13
	v_cndmask_b32_e32 v6, v10, v6, vcc
	v_cndmask_b32_e64 v9, v11, v9, s[42:43]
	v_bfe_u32 v14, v0, 29, 1
	v_cndmask_b32_e64 v5, v5, v6, s[38:39]
	v_alignbit_b32 v11, v0, v9, 30
	v_sub_u32_e32 v15, 0, v14
	v_cndmask_b32_e64 v5, v8, v5, s[40:41]
	v_xor_b32_e32 v11, v11, v15
	v_alignbit_b32 v6, v7, v5, v13
	v_cndmask_b32_e64 v6, v6, v7, s[42:43]
	v_ffbh_u32_e32 v8, v11
	v_alignbit_b32 v7, v9, v6, 30
	v_min_u32_e32 v8, 32, v8
	v_alignbit_b32 v5, v6, v5, 30
	v_xor_b32_e32 v7, v7, v15
	v_sub_u32_e32 v9, 31, v8
	v_xor_b32_e32 v5, v5, v15
	v_alignbit_b32 v10, v11, v7, v9
	v_alignbit_b32 v5, v7, v5, v9
	v_alignbit_b32 v6, v10, v5, 9
	v_ffbh_u32_e32 v7, v6
	v_min_u32_e32 v7, 32, v7
	v_lshrrev_b32_e32 v12, 29, v0
	v_not_b32_e32 v9, v7
	v_alignbit_b32 v5, v6, v5, v9
	v_lshlrev_b32_e32 v6, 31, v12
	v_or_b32_e32 v9, 0x33000000, v6
	v_add_lshl_u32 v7, v7, v8, 23
	v_lshrrev_b32_e32 v5, 9, v5
	v_sub_u32_e32 v7, v9, v7
	v_or_b32_e32 v6, 0.5, v6
	v_lshlrev_b32_e32 v8, 23, v8
	v_or_b32_e32 v5, v7, v5
	v_lshrrev_b32_e32 v7, 9, v10
	v_sub_u32_e32 v6, v6, v8
	v_or_b32_e32 v6, v7, v6
	v_mul_f32_e32 v7, 0x3fc90fda, v6
	s_mov_b32 s12, 0x3fc90fda
	v_fma_f32 v8, v6, s12, -v7
	v_fmac_f32_e32 v8, 0x33a22168, v6
	v_fmac_f32_e32 v8, 0x3fc90fda, v5
	v_lshrrev_b32_e32 v0, 30, v0
	v_add_f32_e32 v60, v7, v8
	v_add_u32_e32 v61, v14, v0

; __device__ __forceinline__ void s5_lane_params(PP p, int l, int g, int n, S5Lane& q) {
;     ...
;     const float lr = p->in[6][gi], li = p->in[7][gi], dt = expf(p->in[8][l * 32 + g]);
;     const float mag = expf(lr * dt);
;     float sn, cs; sincosf(li * dt, &sn, &cs);
;     q.ar = mag * cs; q.ai = mag * sn;
;     const float den = lr * lr + li * li, nr = q.ar - 1.0f, ni = q.ai;
;     const float fr_ = (nr * lr + ni * li) / den, fi_ = (ni * lr - nr * li) / den;
;     const f32x4* bre = (const f32x4*)(p->in[9] + (size_t)gi * 16); const f32x4* bim = (const f32x4*)(p->in[10] + (size_t)gi * 16);
.LBB0_608:
	s_or_b64 exec, exec, s[2:3]
	s_lshr_b32 s2, s21, 25
	s_add_i32 s2, s18, s2
	s_ashr_i32 s34, s2, 7
	s_lshl_b32 s2, s20, 2
	s_nop 0
	v_lshlrev_b64 v[2:3], 6, v[2:3]
	v_ashrrev_i32_e32 v56, 6, v4
	s_sub_i32 s2, s18, s2
	v_lshl_add_u32 v54, s2, 3, v56
	s_waitcnt lgkmcnt(0)
	s_ashr_i32 s35, s34, 31
	v_lshlrev_b32_e32 v2, 6, v54
	s_lshl_b64 s[2:3], s[34:35], 11
	v_ashrrev_i32_e32 v3, 31, v2
	v_lshl_add_u64 v[2:3], s[2:3], 0, v[2:3]
	s_lshl_b32 s2, s9, 4
	s_ashr_i32 s3, s2, 31
	s_lshl_b64 s[2:3], s[2:3], 1
	v_lshrrev_b32_e32 v0, 1, v4
	s_add_u32 s2, s12, s2
	v_and_b32_e32 v0, 8, v0
	s_addc_u32 s3, s13, s3
	v_lshlrev_b32_e32 v0, 1, v0
	v_and_or_b32 v2, v4, 15, v2
	v_lshl_add_u64 v[4:5], s[2:3], 0, v[0:1]
	s_mov_b64 s[2:3], 0x1de00000
	v_lshl_add_u64 v[4:5], v[4:5], 0, s[2:3]
	v_lshlrev_b64 v[2:3], 10, v[2:3]
	v_cmp_gt_u32_e64 s[38:39], 32, v55
	v_mov_b32_e32 v42, 0
	v_lshl_add_u64 v[52:53], v[4:5], 0, v[2:3]
	s_waitcnt vmcnt(12)
	v_mul_f32_e32 v52, v50, v59
	v_mul_f32_e32 v53, 0x3fb8aa3b, v52
	s_mov_b32 s2, 0x3fb8aa3b
	v_fma_f32 v59, v52, s2, -v53
	v_rndne_f32_e32 v62, v53
	v_fmac_f32_e32 v59, 0x32a5705f, v52
	v_sub_f32_e32 v53, v53, v62
	v_add_f32_e32 v53, v53, v59
	v_exp_f32_e32 v53, v53
	v_cvt_i32_f32_e32 v59, v62
	s_mov_b32 s2, 0xc2ce8ed0
	v_cmp_ngt_f32_e32 vcc, s2, v52
	s_mov_b32 s2, 0x42b17218
	v_ldexp_f32 v53, v53, v59
	v_cndmask_b32_e32 v53, 0, v53, vcc
	v_cmp_nlt_f32_e32 vcc, s2, v52
	v_mul_f32_e32 v52, v60, v60
	v_xor_b32_e32 v58, v58, v57
	v_cndmask_b32_e32 v59, v231, v53, vcc
	v_fmamk_f32 v53, v52, 0xb94c1982, v233
	v_fmaak_f32 v53, v52, v53, 0xbe2aaa9d
	v_mul_f32_e32 v53, v52, v53
	v_fmac_f32_e32 v60, v60, v53
	v_fmamk_f32 v53, v52, 0x37d75334, v227
	v_fmaak_f32 v53, v52, v53, 0x3d2aabf7
	v_fmaak_f32 v53, v52, v53, 0xbf000004
	v_fma_f32 v52, v52, v53, 1.0
	v_lshlrev_b32_e32 v53, 30, v61
	v_and_b32_e32 v61, 1, v61
	v_cmp_eq_u32_e32 vcc, 0, v61
	v_readlane_b32 s2, v255, 9
	v_and_b32_e32 v62, 0x80000000, v53
	v_cndmask_b32_e32 v61, v52, v60, vcc
	v_xor_b32_e32 v60, 0x80000000, v60
	v_cndmask_b32_e32 v52, v60, v52, vcc
	v_xor_b32_e32 v58, v58, v61
	v_bitop3_b32 v52, v52, v53, s2 bitop3:0x78
	s_movk_i32 s2, 0x1f8
	v_xor_b32_e32 v58, v58, v62
	v_cmp_class_f32_e64 vcc, v57, s2
	v_readlane_b32 s3, v255, 10
	s_nop 0
	v_cndmask_b32_e32 v57, v234, v52, vcc
	v_cndmask_b32_e32 v52, v234, v58, vcc
	v_mul_f32_e32 v53, v59, v52
	v_fma_f32 v52, v59, v57, -1.0
	v_pk_mul_f32 v[60:61], v[50:51], v[52:53]
	v_mov_b32_e32 v58, v51
	v_add_f32_e32 v62, v60, v61
	v_mov_b32_e32 v60, v53
	v_mov_b32_e32 v61, v50
	v_pk_mul_f32 v[60:61], v[50:51], v[60:61] op_sel_hi:[0,1]
	v_mov_b32_e32 v50, v52
	v_pk_mul_f32 v[50:51], v[58:59], v[50:51] op_sel_hi:[0,1]
	v_add_f32_e32 v51, v61, v51
	v_div_scale_f32 v52, s[2:3], v51, v51, v62
	v_rcp_f32_e32 v58, v52
	v_sub_f32_e32 v50, v60, v50
	v_fma_f32 v61, -v52, v58, 1.0
	v_fmac_f32_e32 v58, v61, v58
	v_div_scale_f32 v61, vcc, v62, v51, v62
	v_mul_f32_e32 v63, v61, v58
	v_fma_f32 v64, -v52, v63, v61
	v_fmac_f32_e32 v63, v64, v58
	v_fma_f32 v52, -v52, v63, v61
	v_div_fmas_f32 v52, v52, v58, v63
	v_div_scale_f32 v58, s[2:3], v51, v51, v50
	v_rcp_f32_e32 v60, v58
	v_div_fixup_f32 v52, v52, v51, v62
	v_fma_f32 v61, -v58, v60, 1.0
	v_fmac_f32_e32 v60, v61, v60
	v_div_scale_f32 v61, vcc, v50, v51, v50
	v_mul_f32_e32 v62, v61, v60
	v_fma_f32 v63, -v58, v62, v61
	v_fmac_f32_e32 v62, v63, v60
	v_fma_f32 v58, -v58, v62, v61
	v_div_fmas_f32 v58, v58, v60, v62
	v_div_fixup_f32 v50, v58, v51, v50
	s_waitcnt vmcnt(0)
; __device__ __forceinline__ void s5_lane_params(PP p, int l, int g, int n, S5Lane& q) {
;     ...
;     const f32x4* bre = (const f32x4*)(p->in[9] + (size_t)gi * 16); const f32x4* bim = (const f32x4*)(p->in[10] + (size_t)gi * 16);
; #pragma unroll
;     for (int c4 = 0; c4 < 4; ++c4) { const f32x4 br = bre[c4], bi = bim[c4];
; #pragma unroll
;         for (int e = 0; e < 4; ++e) { q.bb[c4 * 4 + e] = (f32x2){fr_ * br[e] - fi_ * bi[e], fr_ * bi[e] + fi_ * br[e]}; } }
; }
; __device__ __forceinline__ void s5_load_u(const bf16_t* proj, int b, int l0, int g, float* ub, int lane) {
;     const bf16_t* src = proj + PJ_UA + (size_t)(b * SEQ + l0 + lane) * 512 + g * 16;
;     const u32x4 a = *(const u32x4*)src, c = *(const u32x4*)(src + 8);
;     f32x4* d = (f32x4*)(ub + lane * 16);
;     d[0] = (f32x4){__uint_as_float(a.x << 16), __uint_as_float(a.x & 0xffff0000u), __uint_as_float(a.y << 16), __uint_as_float(a.y & 0xffff0000u)};
;     d[1] = (f32x4){__uint_as_float(a.z << 16), __uint_as_float(a.z & 0xffff0000u), __uint_as_float(a.w << 16), __uint_as_float(a.w & 0xffff0000u)};
;     d[2] = (f32x4){__uint_as_float(c.x << 16), __uint_as_float(c.x & 0xffff0000u), __uint_as_float(c.y << 16), __uint_as_float(c.y & 0xffff0000u)};
;     d[3] = (f32x4){__uint_as_float(c.z << 16), __uint_as_float(c.z & 0xffff0000u), __uint_as_float(c.w << 16), __uint_as_float(c.w & 0xffff0000u)};
; }
; __device__ __forceinline__ void s5_step(const S5Lane& q, const float* urow, f32x2& x) {
;     const f32x4* u4 = (const f32x4*)urow;
;     f32x2 b0 = (f32x2){0.f, 0.f}, b1 = b0;
; #pragma unroll
;     for (int c4 = 0; c4 < 4; ++c4) { const f32x4 uv = u4[c4];
;         b0 += q.bb[c4 * 4 + 0] * uv[0]; b1 += q.bb[c4 * 4 + 1] * uv[1]; b0 += q.bb[c4 * 4 + 2] * uv[2]; b1 += q.bb[c4 * 4 + 3] * uv[3]; }
;     const f32x2 rot = (f32x2){-x.y, x.x};
;     x = (x * q.ar + rot * q.ai) + (b0 + b1);
; }
; __device__ __forceinline__ void s5_write_bbl(const S5Lane& q, bf16_t* bbL, int lane) {
;     u32x4 re0, re1, im0, im1;
;     re0.x = pk2(q.bb[0].x, q.bb[1].x); re0.y = pk2(q.bb[2].x, q.bb[3].x); re0.z = pk2(q.bb[4].x, q.bb[5].x); re0.w = pk2(q.bb[6].x, q.bb[7].x);
;     re1.x = pk2(q.bb[8].x, q.bb[9].x); re1.y = pk2(q.bb[10].x, q.bb[11].x); re1.z = pk2(q.bb[12].x, q.bb[13].x); re1.w = pk2(q.bb[14].x, q.bb[15].x);
	v_mov_b32_e32 v14, v130
	v_mov_b32_e32 v15, v131
	v_mov_b32_e32 v16, v132
	v_mov_b32_e32 v17, v133
	v_mov_b32_e32 v26, v134
	v_mov_b32_e32 v27, v135
	v_mov_b32_e32 v28, v136
	v_mov_b32_e32 v29, v137
	v_mov_b32_e32 v34, v138
	v_mov_b32_e32 v35, v139
	v_mov_b32_e32 v36, v140
	v_mov_b32_e32 v37, v141
	v_mov_b32_e32 v38, v142
	v_mov_b32_e32 v39, v143
	v_mov_b32_e32 v40, v144
	v_mov_b32_e32 v41, v145
	v_mov_b32_e32 v6, v146
	v_mov_b32_e32 v7, v147
	v_mov_b32_e32 v8, v148
	v_mov_b32_e32 v9, v149
	v_mov_b32_e32 v10, v150
	v_mov_b32_e32 v11, v151
	v_mov_b32_e32 v12, v152
	v_mov_b32_e32 v13, v153
	v_mov_b32_e32 v18, v154
	v_mov_b32_e32 v19, v155
	v_mov_b32_e32 v20, v156
	v_mov_b32_e32 v21, v157
	v_mov_b32_e32 v22, v158
	v_mov_b32_e32 v23, v159
	v_mov_b32_e32 v24, v160
	v_mov_b32_e32 v25, v161
	v_mov_b32_e32 v46, v162
	v_mov_b32_e32 v47, v163
	v_mov_b32_e32 v48, v164
	v_mov_b32_e32 v49, v165
	v_mov_b32_e32 v42, v166
	v_mov_b32_e32 v43, v167
	v_mov_b32_e32 v44, v168
	v_mov_b32_e32 v45, v169
	v_mov_b32_e32 v30, v170
	v_mov_b32_e32 v31, v171
	v_mov_b32_e32 v32, v172
	v_mov_b32_e32 v33, v173
	v_mov_b32_e32 v2, v174
	v_mov_b32_e32 v3, v175
	v_mov_b32_e32 v4, v176
	v_mov_b32_e32 v5, v177
	v_pk_mul_f32 v[60:61], v[22:23], v[50:51] op_sel_hi:[1,0]
	v_pk_mul_f32 v[62:63], v[24:25], v[50:51] op_sel_hi:[1,0]
	v_pk_fma_f32 v[60:61], v[38:39], v[52:53], v[60:61] op_sel_hi:[1,0,1] neg_lo:[0,0,1] neg_hi:[0,0,1]
	v_pk_mul_f32 v[38:39], v[38:39], v[50:51] op_sel_hi:[1,0]
	v_pk_mul_f32 v[64:65], v[18:19], v[50:51] op_sel_hi:[1,0]
	v_pk_mul_f32 v[66:67], v[20:21], v[50:51] op_sel_hi:[1,0]
	v_pk_mul_f32 v[68:69], v[10:11], v[50:51] op_sel_hi:[1,0]
	v_pk_mul_f32 v[70:71], v[12:13], v[50:51] op_sel_hi:[1,0]
	v_pk_mul_f32 v[72:73], v[6:7], v[50:51] op_sel_hi:[1,0]
	v_pk_mul_f32 v[74:75], v[8:9], v[50:51] op_sel_hi:[1,0]
	v_pk_fma_f32 v[62:63], v[40:41], v[52:53], v[62:63] op_sel_hi:[1,0,1] neg_lo:[0,0,1] neg_hi:[0,0,1]
	v_pk_mul_f32 v[40:41], v[40:41], v[50:51] op_sel_hi:[1,0]
	v_pk_fma_f32 v[64:65], v[34:35], v[52:53], v[64:65] op_sel_hi:[1,0,1] neg_lo:[0,0,1] neg_hi:[0,0,1]
	v_pk_mul_f32 v[34:35], v[34:35], v[50:51] op_sel_hi:[1,0]
	v_pk_fma_f32 v[66:67], v[36:37], v[52:53], v[66:67] op_sel_hi:[1,0,1] neg_lo:[0,0,1] neg_hi:[0,0,1]
	v_pk_mul_f32 v[36:37], v[36:37], v[50:51] op_sel_hi:[1,0]
	v_pk_fma_f32 v[68:69], v[26:27], v[52:53], v[68:69] op_sel_hi:[1,0,1] neg_lo:[0,0,1] neg_hi:[0,0,1]
	v_pk_mul_f32 v[26:27], v[26:27], v[50:51] op_sel_hi:[1,0]
	v_pk_fma_f32 v[70:71], v[28:29], v[52:53], v[70:71] op_sel_hi:[1,0,1] neg_lo:[0,0,1] neg_hi:[0,0,1]
	v_pk_mul_f32 v[28:29], v[28:29], v[50:51] op_sel_hi:[1,0]
	v_pk_fma_f32 v[72:73], v[14:15], v[52:53], v[72:73] op_sel_hi:[1,0,1] neg_lo:[0,0,1] neg_hi:[0,0,1]
	v_pk_mul_f32 v[14:15], v[14:15], v[50:51] op_sel_hi:[1,0]
	v_pk_fma_f32 v[74:75], v[16:17], v[52:53], v[74:75] op_sel_hi:[1,0,1] neg_lo:[0,0,1] neg_hi:[0,0,1]
	v_pk_mul_f32 v[16:17], v[16:17], v[50:51] op_sel_hi:[1,0]
	v_pk_fma_f32 v[22:23], v[22:23], v[52:53], v[38:39] op_sel_hi:[1,0,1]
	v_lshlrev_b32_e32 v51, 5, v55
	v_pk_fma_f32 v[24:25], v[24:25], v[52:53], v[40:41] op_sel_hi:[1,0,1]
	v_pk_fma_f32 v[18:19], v[18:19], v[52:53], v[34:35] op_sel_hi:[1,0,1]
	v_pk_fma_f32 v[20:21], v[20:21], v[52:53], v[36:37] op_sel_hi:[1,0,1]
	v_pk_fma_f32 v[26:27], v[10:11], v[52:53], v[26:27] op_sel_hi:[1,0,1]
	v_pk_fma_f32 v[28:29], v[12:13], v[52:53], v[28:29] op_sel_hi:[1,0,1]
	v_pk_fma_f32 v[34:35], v[6:7], v[52:53], v[14:15] op_sel_hi:[1,0,1]
	v_pk_fma_f32 v[36:37], v[8:9], v[52:53], v[16:17] op_sel_hi:[1,0,1]
	v_cvt_pk_bf16_f32 v6, v60, v61
	v_cvt_pk_bf16_f32 v7, v62, v63
	v_cvt_pk_bf16_f32 v8, v64, v65
	v_cvt_pk_bf16_f32 v9, v66, v67
	v_cvt_pk_bf16_f32 v14, v22, v23
	v_add_u32_e32 v22, 0, v51
	v_cvt_pk_bf16_f32 v10, v68, v69
	v_cvt_pk_bf16_f32 v11, v70, v71
	v_cvt_pk_bf16_f32 v12, v72, v73
	v_cvt_pk_bf16_f32 v13, v74, v75
	v_cvt_pk_bf16_f32 v15, v24, v25
	v_cvt_pk_bf16_f32 v16, v18, v19
	v_cvt_pk_bf16_f32 v17, v20, v21
	v_cvt_pk_bf16_f32 v18, v26, v27
	v_cvt_pk_bf16_f32 v19, v28, v29
	v_cvt_pk_bf16_f32 v20, v34, v35
	v_cvt_pk_bf16_f32 v21, v36, v37
	ds_write_b128 v22, v[6:9]
	ds_write_b128 v22, v[10:13] offset:16
	ds_write_b128 v22, v[14:17] offset:2048
	ds_write_b128 v22, v[18:21] offset:2064
	v_and_b32_e32 v6, 0x1e0, v51
	v_add3_u32 v0, 0, v6, v0
	v_mov_b32_e32 v6, 0
	v_mov_b32_e32 v26, 0
	v_mov_b32_e32 v27, 0
	v_mov_b32_e32 v28, 0
	v_mov_b32_e32 v29, 0
	v_mov_b32_e32 v14, 0
	v_mov_b32_e32 v15, 0
	v_mov_b32_e32 v16, 0
	v_mov_b32_e32 v17, 0
	s_waitcnt lgkmcnt(0)
	s_barrier
	s_and_saveexec_b64 s[2:3], s[38:39]
	s_xor_b64 s[2:3], exec, s[2:3]
	s_cbranch_execz .LBB0_618
	ds_read_b128 v[26:29], v0
	ds_read_b128 v[14:17], v0 offset:512

; __device__ __forceinline__ int tid_fresh() { int t = threadIdx.x; asm volatile("" : "+v"(t)); return t; }
; __device__ __forceinline__ void s5_lane_params(PP p, int l, int g, int n, S5Lane& q) {
;     const int gi = (l * 32 + g) * 64 + n;
;     const float lr = p->in[6][gi], li = p->in[7][gi], dt = expf(p->in[8][l * 32 + g]);
;     const float mag = expf(lr * dt);
;     float sn, cs; sincosf(li * dt, &sn, &cs);
;     q.ar = mag * cs; q.ai = mag * sn;
;     const float den = lr * lr + li * li, nr = q.ar - 1.0f, ni = q.ai;
;     const float fr_ = (nr * lr + ni * li) / den, fi_ = (ni * lr - nr * li) / den;
;     const f32x4* bre = (const f32x4*)(p->in[9] + (size_t)gi * 16); const f32x4* bim = (const f32x4*)(p->in[10] + (size_t)gi * 16);
; __device__ __forceinline__ void s5_pass2_item(PP p, unsigned char* shm, int item, int l) {
;     const int tid = tid_fresh(), w = tid >> 6, lane = tid & 63;
;     const int b = item / 128, g = (item / 4) % 32, jg = item % 4, j = jg * 8 + w;
;     const bf16_t* proj = (const bf16_t*)(p->ws + WS_PROJ);
;     bf16_t* bbL = (bf16_t*)(shm + S5_BBL); float* buL = (float*)(shm + S5_BUL) + w * 2048; float* xs = (float*)(shm + S5_XS) + w * (16 * 132);
;     const int cc = lane & 15, quad = lane >> 4;
;     float cmr[32];
;     { const float* src = ((quad < 2) ? p->in[11] : p->in[12]) + ((size_t)(l * 32 + g) * 16 + cc) * 64 + (quad & 1) * 32;
;       const float sgn = (quad < 2) ? 1.0f : -1.0f;
; #pragma unroll
;       for (int i = 0; i < 8; ++i) { const f32x4 v = *(const f32x4*)(src + 4 * i); cmr[4 * i] = v[0] * sgn; cmr[4 * i + 1] = v[1] * sgn; cmr[4 * i + 2] = v[2] * sgn; cmr[4 * i + 3] = v[3] * sgn; } }
;     S5Lane q; s5_lane_params(p, l, g, lane, q);
;     const size_t row0 = (size_t)b * SEQ + j * 64;
;     bf16x8 uf[4];
; #pragma unroll
;     for (int sc = 0; sc < 4; ++sc) uf[sc] = s5_ufrag(proj, row0 + sc * 16, g, lane);
.LBB0_680:
	s_mov_b64 s[12:13], s[0:1]
	v_mov_b32_e32 v92, v222
	s_load_dwordx2 s[44:45], s[12:13], 0x58
	s_load_dwordx2 s[52:53], s[12:13], 0x60
	s_load_dwordx4 s[20:23], s[12:13], 0x30
	s_load_dwordx2 s[24:25], s[12:13], 0x40
	s_load_dwordx4 s[40:43], s[12:13], 0x48
	s_load_dwordx2 s[28:29], s[12:13], 0x110
	v_and_b32_e32 v98, 63, v92
	v_cmp_gt_u32_e64 s[38:39], 32, v98
	s_ashr_i32 s8, s14, 31
	s_lshr_b32 s2, s8, 30
	s_add_i32 s2, s14, s2
	s_ashr_i32 s9, s2, 2
	s_ashr_i32 s2, s2, 31
	s_lshr_b32 s2, s2, 27
	s_add_i32 s2, s9, s2
	s_andn2_b32 s2, s2, 31
	s_sub_i32 s16, s9, s2
	s_add_i32 s2, s16, s54
	s_ashr_i32 s3, s2, 31
	v_and_b32_e32 v100, 15, v92
	s_lshl_b64 s[34:35], s[2:3], 12
	v_lshlrev_b32_e32 v0, 8, v100
	s_waitcnt lgkmcnt(0)
	v_mov_b32_e32 v2, s52
	v_mov_b32_e32 v3, s53
	v_mov_b32_e32 v4, s44
	v_mov_b32_e32 v5, s45
	v_cndmask_b32_e64 v2, v2, v4, s[38:39]
	v_cndmask_b32_e64 v3, v3, v5, s[38:39]
	v_lshl_add_u64 v[2:3], v[2:3], 0, s[34:35]
	v_lshl_add_u64 v[2:3], v[2:3], 0, v[0:1]
	v_lshlrev_b32_e32 v0, 3, v92
	v_and_b32_e32 v0, 0x80, v0
	v_lshl_add_u64 v[2:3], v[2:3], 0, v[0:1]
	global_load_dwordx4 v[58:61], v[2:3], off offset:48
	global_load_dwordx4 v[54:57], v[2:3], off offset:32
	global_load_dwordx4 v[50:53], v[2:3], off offset:16
	global_load_dwordx4 v[46:49], v[2:3], off
	global_load_dwordx4 v[74:77], v[2:3], off offset:112
	global_load_dwordx4 v[70:73], v[2:3], off offset:96
	global_load_dwordx4 v[66:69], v[2:3], off offset:80
	global_load_dwordx4 v[62:65], v[2:3], off offset:64
	v_lshl_or_b32 v2, s2, 6, v98
	s_lshl_b64 s[2:3], s[2:3], 2
	v_ashrrev_i32_e32 v3, 31, v2
	v_lshlrev_b64 v[4:5], 2, v[2:3]
	s_add_u32 s2, s24, s2
	s_addc_u32 s3, s25, s3
	global_load_dword v0, v1, s[2:3]
	v_lshl_add_u64 v[6:7], s[20:21], 0, v[4:5]
	v_lshl_add_u64 v[4:5], s[22:23], 0, v[4:5]
	global_load_dword v91, v[4:5], off
	global_load_dword v90, v[6:7], off
	v_lshlrev_b64 v[212:213], 6, v[2:3]
	v_lshl_add_u64 v[214:215], s[40:41], 0, v[212:213]
	v_lshl_add_u64 v[212:213], s[42:43], 0, v[212:213]
	global_load_dwordx4 v[130:133], v[214:215], off offset:48
	global_load_dwordx4 v[134:137], v[214:215], off offset:32
	global_load_dwordx4 v[138:141], v[214:215], off offset:16
	global_load_dwordx4 v[142:145], v[214:215], off
	global_load_dwordx4 v[146:149], v[212:213], off offset:48
	global_load_dwordx4 v[150:153], v[212:213], off offset:32
	global_load_dwordx4 v[154:157], v[212:213], off offset:16
	global_load_dwordx4 v[158:161], v[212:213], off
	s_lshr_b32 s34, s8, 25
	s_add_i32 s34, s14, s34
	s_ashr_i32 s34, s34, 7
	s_ashr_i32 s35, s34, 31
	s_lshl_b64 s[34:35], s[34:35], 11
	s_lshl_b32 s98, s9, 2
	s_sub_i32 s98, s14, s98
	v_ashrrev_i32_e32 v216, 6, v92
	v_lshl_add_u32 v216, s98, 3, v216
	v_lshlrev_b32_e32 v216, 6, v216
	v_ashrrev_i32_e32 v217, 31, v216
	v_lshl_add_u64 v[216:217], s[34:35], 0, v[216:217]
	s_lshl_b32 s34, s16, 4
	s_ashr_i32 s35, s34, 31
	s_lshl_b64 s[34:35], s[34:35], 1
	s_add_u32 s34, s28, s34
	s_addc_u32 s35, s29, s35
	s_add_u32 s34, s34, 0x1de00000
	s_addc_u32 s35, s35, 0
	v_lshrrev_b32_e32 v218, 1, v92
	v_and_b32_e32 v218, 8, v218
	v_lshlrev_b32_e32 v218, 1, v218
	v_mov_b32_e32 v219, 0
	v_lshl_add_u64 v[218:219], s[34:35], 0, v[218:219]
	v_mov_b32_e32 v162, 0
	v_mov_b32_e32 v163, 0
	v_mov_b32_e32 v164, 0
	v_mov_b32_e32 v165, 0
	v_mov_b32_e32 v166, 0
	v_mov_b32_e32 v167, 0
	v_mov_b32_e32 v168, 0
	v_mov_b32_e32 v169, 0
	v_mov_b32_e32 v170, 0
	v_mov_b32_e32 v171, 0
	v_mov_b32_e32 v172, 0
	v_mov_b32_e32 v173, 0
	v_mov_b32_e32 v174, 0
	v_mov_b32_e32 v175, 0
	v_mov_b32_e32 v176, 0
	v_mov_b32_e32 v177, 0
	s_and_saveexec_b64 s[34:35], s[38:39]
	v_or_b32_e32 v220, v216, v100
	v_mov_b32_e32 v221, v217
	v_lshlrev_b64 v[220:221], 10, v[220:221]
	v_lshl_add_u64 v[220:221], v[218:219], 0, v[220:221]
	global_load_dwordx4 v[162:165], v[220:221], off
	v_or3_b32 v220, v100, v216, 16
	v_mov_b32_e32 v221, v217
	v_lshlrev_b64 v[220:221], 10, v[220:221]
	v_lshl_add_u64 v[220:221], v[218:219], 0, v[220:221]
	global_load_dwordx4 v[166:169], v[220:221], off
	v_or3_b32 v220, v100, v216, 32
	v_mov_b32_e32 v221, v217
	v_lshlrev_b64 v[220:221], 10, v[220:221]
	v_lshl_add_u64 v[220:221], v[218:219], 0, v[220:221]
	global_load_dwordx4 v[170:173], v[220:221], off
	v_or3_b32 v220, v100, v216, 48
	v_mov_b32_e32 v221, v217
	v_lshlrev_b64 v[220:221], 10, v[220:221]
	v_lshl_add_u64 v[220:221], v[218:219], 0, v[220:221]
	global_load_dwordx4 v[174:177], v[220:221], off
	s_or_b64 exec, exec, s[34:35]
	s_mov_b32 s2, 0x3fb8aa3b
	s_waitcnt vmcnt(14)
	v_mul_f32_e32 v4, 0x3fb8aa3b, v0
	v_fma_f32 v5, v0, s2, -v4
	v_rndne_f32_e32 v6, v4
	v_fmac_f32_e32 v5, 0x32a5705f, v0
	v_sub_f32_e32 v4, v4, v6
	v_add_f32_e32 v4, v4, v5
	v_exp_f32_e32 v4, v4
	v_cvt_i32_f32_e32 v5, v6
	s_mov_b32 s2, 0xc2ce8ed0
	v_cmp_ngt_f32_e32 vcc, s2, v0
	s_mov_b32 s2, 0x42b17218
	v_ldexp_f32 v4, v4, v5
	v_cndmask_b32_e32 v4, 0, v4, vcc
	v_cmp_nlt_f32_e32 vcc, s2, v0
	s_brev_b32 s2, 18
	s_nop 0
	v_cndmask_b32_e32 v87, v231, v4, vcc
	s_waitcnt vmcnt(13)
	v_mul_f32_e32 v86, v91, v87
	v_and_b32_e32 v88, 0x7fffffff, v86
	v_cmp_nlt_f32_e64 s[2:3], |v86|, s2
	s_and_saveexec_b64 s[20:21], s[2:3]
	s_xor_b64 s[2:3], exec, s[20:21]
	s_cbranch_execz .LBB0_682
; __device__ __forceinline__ void s5_lane_params(PP p, int l, int g, int n, S5Lane& q) {
;     ...
;     const float lr = p->in[6][gi], li = p->in[7][gi], dt = expf(p->in[8][l * 32 + g]);
;     const float mag = expf(lr * dt);
;     float sn, cs; sincosf(li * dt, &sn, &cs);
;     q.ar = mag * cs; q.ai = mag * sn;
;     const float den = lr * lr + li * li, nr = q.ar - 1.0f, ni = q.ai;
;     const float fr_ = (nr * lr + ni * li) / den, fi_ = (ni * lr - nr * li) / den;
	v_lshrrev_b32_e32 v0, 23, v88
	v_add_u32_e32 v0, 0xffffff88, v0
	v_cmp_lt_u32_e32 vcc, 63, v0
	v_not_b32_e32 v4, 63
	v_not_b32_e32 v5, 31
	v_cndmask_b32_e32 v4, 0, v4, vcc
	v_add_u32_e32 v0, v4, v0
	v_cmp_lt_u32_e64 s[40:41], 31, v0
	s_mov_b32 s17, 0xfe5163ab
	s_nop 0
	v_cndmask_b32_e64 v4, 0, v5, s[40:41]
	v_add_u32_e32 v0, v4, v0
	v_cmp_lt_u32_e64 s[42:43], 31, v0
	s_nop 1
	v_cndmask_b32_e64 v4, 0, v5, s[42:43]
	v_add_u32_e32 v18, v4, v0
	v_and_b32_e32 v0, 0x7fffff, v88
	v_or_b32_e32 v16, 0x800000, v0
	v_mad_u64_u32 v[4:5], s[20:21], v16, s17, 0
	v_mov_b32_e32 v0, v5
	s_mov_b32 s17, 0x3c439041
	v_mad_u64_u32 v[6:7], s[20:21], v16, s17, v[0:1]
	v_mov_b32_e32 v0, v7
	s_mov_b32 s17, 0xdb629599
	v_mad_u64_u32 v[8:9], s[20:21], v16, s17, v[0:1]
	v_mov_b32_e32 v0, v9
	s_mov_b32 s17, 0xf534ddc0
	v_mad_u64_u32 v[10:11], s[20:21], v16, s17, v[0:1]
	v_mov_b32_e32 v0, v11
	s_mov_b32 s17, 0xfc2757d1
	v_mad_u64_u32 v[12:13], s[20:21], v16, s17, v[0:1]
	v_mov_b32_e32 v0, v13
	s_mov_b32 s17, 0x4e441529
	v_mad_u64_u32 v[14:15], s[20:21], v16, s17, v[0:1]
	v_mov_b32_e32 v0, v15
	s_mov_b32 s17, 0xa2f9836e
	v_mad_u64_u32 v[16:17], s[20:21], v16, s17, v[0:1]
	v_cndmask_b32_e32 v5, v14, v10, vcc
	v_cndmask_b32_e32 v0, v16, v12, vcc
	v_cndmask_b32_e32 v9, v17, v14, vcc
	v_cndmask_b32_e64 v7, v0, v5, s[40:41]
	v_cndmask_b32_e64 v0, v9, v0, s[40:41]
	v_cndmask_b32_e32 v9, v12, v8, vcc
	v_cndmask_b32_e64 v5, v5, v9, s[40:41]
	v_cndmask_b32_e32 v6, v10, v6, vcc
	v_cndmask_b32_e64 v0, v0, v7, s[42:43]
	v_cndmask_b32_e64 v7, v7, v5, s[42:43]
	v_sub_u32_e32 v11, 32, v18
	v_cndmask_b32_e64 v9, v9, v6, s[40:41]
	v_alignbit_b32 v12, v0, v7, v11
	v_cmp_eq_u32_e64 s[44:45], 0, v18
	v_cndmask_b32_e64 v5, v5, v9, s[42:43]
	v_cndmask_b32_e32 v4, v8, v4, vcc
	v_cndmask_b32_e64 v0, v12, v0, s[44:45]
	v_alignbit_b32 v10, v7, v5, v11
	v_cndmask_b32_e64 v4, v6, v4, s[40:41]
	v_cndmask_b32_e64 v7, v10, v7, s[44:45]
	v_bfe_u32 v13, v0, 29, 1
	v_cndmask_b32_e64 v4, v9, v4, s[42:43]
	v_alignbit_b32 v10, v0, v7, 30
	v_sub_u32_e32 v14, 0, v13
	v_alignbit_b32 v6, v5, v4, v11
	v_xor_b32_e32 v10, v10, v14
	v_cndmask_b32_e64 v5, v6, v5, s[44:45]
	v_alignbit_b32 v6, v7, v5, 30
	v_ffbh_u32_e32 v7, v10
	v_min_u32_e32 v7, 32, v7
	v_alignbit_b32 v4, v5, v4, 30
	v_xor_b32_e32 v6, v6, v14
	v_sub_u32_e32 v8, 31, v7
	v_xor_b32_e32 v4, v4, v14
	v_alignbit_b32 v9, v10, v6, v8
	v_alignbit_b32 v4, v6, v4, v8
	v_alignbit_b32 v5, v9, v4, 9
	v_ffbh_u32_e32 v6, v5
	v_min_u32_e32 v6, 32, v6
	v_lshrrev_b32_e32 v12, 29, v0
	v_not_b32_e32 v8, v6
	v_alignbit_b32 v4, v5, v4, v8
	v_lshlrev_b32_e32 v5, 31, v12
	v_or_b32_e32 v8, 0x33000000, v5
	v_add_lshl_u32 v6, v6, v7, 23
	v_lshrrev_b32_e32 v4, 9, v4
	v_sub_u32_e32 v6, v8, v6
	v_or_b32_e32 v5, 0.5, v5
	v_lshlrev_b32_e32 v7, 23, v7
	v_or_b32_e32 v4, v6, v4
	v_lshrrev_b32_e32 v6, 9, v9
	v_sub_u32_e32 v5, v5, v7
	v_or_b32_e32 v5, v6, v5
	v_mul_f32_e32 v6, 0x3fc90fda, v5
	s_mov_b32 s17, 0x3fc90fda
	v_fma_f32 v7, v5, s17, -v6
	v_fmac_f32_e32 v7, 0x33a22168, v5
	v_fmac_f32_e32 v7, 0x3fc90fda, v4
	v_lshrrev_b32_e32 v0, 30, v0
	v_add_f32_e32 v89, v6, v7
	v_add_u32_e32 v95, v13, v0
.LBB0_682:
	s_or_saveexec_b64 s[2:3], s[2:3]
	s_nop 0
	s_xor_b64 exec, exec, s[2:3]
	s_cbranch_execz .LBB0_684
	s_mov_b32 s17, 0x3f22f983
	v_mul_f32_e64 v0, |v86|, s17
	v_rndne_f32_e32 v0, v0
	v_cvt_i32_f32_e32 v95, v0
	s_mov_b32 s17, 0xbfc90fda
	v_fma_f32 v89, v0, s17, |v86|
	v_fmac_f32_e32 v89, 0xb3a22168, v0
	v_fmac_f32_e32 v89, 0xa7c234c4, v0
.LBB0_684:
	s_or_b64 exec, exec, s[2:3]
	s_nop 0
	v_lshlrev_b64 v[2:3], 6, v[2:3]
	s_lshr_b32 s3, s8, 25
	s_lshl_b32 s2, s9, 2
	s_add_i32 s3, s14, s3
	s_waitcnt lgkmcnt(0)
	v_ashrrev_i32_e32 v93, 6, v92
	s_sub_i32 s2, s14, s2
	s_ashr_i32 s40, s3, 7
	v_lshl_add_u32 v94, s2, 3, v93
	s_add_u32 s8, s28, 0x1de00000
	s_addc_u32 s9, s29, 0
	s_ashr_i32 s41, s40, 31
	v_lshlrev_b32_e32 v2, 6, v94
	s_lshl_b32 s34, s16, 4
	s_lshl_b64 s[2:3], s[40:41], 11
	v_ashrrev_i32_e32 v3, 31, v2
	s_ashr_i32 s35, s34, 31
	v_lshl_add_u64 v[82:83], s[2:3], 0, v[2:3]
	s_lshl_b64 s[2:3], s[34:35], 1
	v_lshrrev_b32_e32 v0, 1, v92
	s_add_u32 s2, s8, s2
	v_and_b32_e32 v0, 8, v0
	s_addc_u32 s3, s9, s3
	v_lshlrev_b32_e32 v0, 1, v0
	v_lshl_add_u64 v[84:85], s[2:3], 0, v[0:1]
	s_waitcnt vmcnt(12)
	v_mul_f32_e32 v84, v90, v87
	v_mul_f32_e32 v85, 0x3fb8aa3b, v84
	s_mov_b32 s2, 0x3fb8aa3b
	v_fma_f32 v87, v84, s2, -v85
	v_rndne_f32_e32 v96, v85
	v_fmac_f32_e32 v87, 0x32a5705f, v84
	v_sub_f32_e32 v85, v85, v96
	v_add_f32_e32 v85, v85, v87
	v_exp_f32_e32 v85, v85
	v_cvt_i32_f32_e32 v87, v96
	s_mov_b32 s2, 0xc2ce8ed0
	v_cmp_ngt_f32_e32 vcc, s2, v84
	s_mov_b32 s2, 0x42b17218
	v_ldexp_f32 v85, v85, v87
	v_cndmask_b32_e32 v85, 0, v85, vcc
	v_cmp_nlt_f32_e32 vcc, s2, v84
	v_mul_f32_e32 v84, v89, v89
	v_fmamk_f32 v96, v84, 0xb94c1982, v233
	v_fmaak_f32 v96, v84, v96, 0xbe2aaa9d
	v_mul_f32_e32 v96, v84, v96
	v_fmac_f32_e32 v89, v89, v96
	v_fmamk_f32 v96, v84, 0x37d75334, v227
	v_fmaak_f32 v96, v84, v96, 0x3d2aabf7
	v_fmaak_f32 v96, v84, v96, 0xbf000004
	v_fma_f32 v84, v84, v96, 1.0
	v_lshlrev_b32_e32 v96, 30, v95
	v_and_b32_e32 v95, 1, v95
	v_cndmask_b32_e32 v85, v231, v85, vcc
	v_cmp_eq_u32_e32 vcc, 0, v95
	v_xor_b32_e32 v88, v88, v86
	v_readlane_b32 s2, v255, 9
	v_cndmask_b32_e32 v95, v84, v89, vcc
	v_xor_b32_e32 v89, 0x80000000, v89
	v_cndmask_b32_e32 v84, v89, v84, vcc
	v_and_b32_e32 v97, 0x80000000, v96
	v_xor_b32_e32 v88, v88, v95
	v_bitop3_b32 v84, v84, v96, s2 bitop3:0x78
	s_movk_i32 s2, 0x1f8
	v_xor_b32_e32 v88, v88, v97
	v_cmp_class_f32_e64 vcc, v86, s2
	v_mov_b32_e32 v87, 0
	v_readlane_b32 s3, v255, 10
	v_cndmask_b32_e32 v86, v234, v84, vcc
	v_cndmask_b32_e32 v88, v234, v88, vcc
	v_mul_f32_e32 v89, v85, v88
	v_fma_f32 v88, v85, v86, -1.0
	v_pk_mul_f32 v[96:97], v[90:91], v[88:89]
	v_mul_f32_e32 v84, v85, v86
	v_add_f32_e32 v85, v96, v97
	v_mov_b32_e32 v96, v89
	v_mov_b32_e32 v97, v90
	v_pk_mul_f32 v[96:97], v[90:91], v[96:97] op_sel_hi:[0,1]
	v_mov_b32_e32 v86, v91
	v_mov_b32_e32 v90, v88
	v_pk_mul_f32 v[90:91], v[86:87], v[90:91] op_sel_hi:[0,1]
	v_add_f32_e32 v88, v97, v91
	v_div_scale_f32 v86, s[2:3], v88, v88, v85
	v_rcp_f32_e32 v91, v86
	s_nop 0
	v_fma_f32 v95, -v86, v91, 1.0
	v_fmac_f32_e32 v91, v95, v91
	v_div_scale_f32 v95, vcc, v85, v88, v85
	v_mul_f32_e32 v97, v95, v91
	v_fma_f32 v99, -v86, v97, v95
	v_fmac_f32_e32 v97, v99, v91
	v_fma_f32 v86, -v86, v97, v95
	v_div_fmas_f32 v86, v86, v91, v97
	v_div_fixup_f32 v86, v86, v88, v85
	v_sub_f32_e32 v85, v96, v90
	v_div_scale_f32 v90, s[2:3], v88, v88, v85
	v_rcp_f32_e32 v91, v90
	v_lshlrev_b32_e32 v99, 5, v98
	v_fma_f32 v95, -v90, v91, 1.0
	v_fmac_f32_e32 v91, v95, v91
	v_div_scale_f32 v95, vcc, v85, v88, v85
	v_mul_f32_e32 v96, v95, v91
	v_fma_f32 v97, -v90, v96, v95
	v_fmac_f32_e32 v96, v97, v91
	v_fma_f32 v90, -v90, v96, v95
	v_div_fmas_f32 v90, v90, v91, v96
	v_div_fixup_f32 v88, v90, v88, v85
	s_waitcnt vmcnt(0)
; __device__ __forceinline__ void s5_lane_params(PP p, int l, int g, int n, S5Lane& q) {
;     ...
;     const f32x4* bre = (const f32x4*)(p->in[9] + (size_t)gi * 16); const f32x4* bim = (const f32x4*)(p->in[10] + (size_t)gi * 16);
; #pragma unroll
;     for (int c4 = 0; c4 < 4; ++c4) { const f32x4 br = bre[c4], bi = bim[c4];
; #pragma unroll
;         for (int e = 0; e < 4; ++e) { q.bb[c4 * 4 + e] = (f32x2){fr_ * br[e] - fi_ * bi[e], fr_ * bi[e] + fi_ * br[e]}; } }
; }
; __device__ __forceinline__ void s5_load_u(const bf16_t* proj, int b, int l0, int g, float* ub, int lane) {
;     const bf16_t* src = proj + PJ_UA + (size_t)(b * SEQ + l0 + lane) * 512 + g * 16;
;     const u32x4 a = *(const u32x4*)src, c = *(const u32x4*)(src + 8);
;     f32x4* d = (f32x4*)(ub + lane * 16);
;     d[0] = (f32x4){__uint_as_float(a.x << 16), __uint_as_float(a.x & 0xffff0000u), __uint_as_float(a.y << 16), __uint_as_float(a.y & 0xffff0000u)};
;     d[1] = (f32x4){__uint_as_float(a.z << 16), __uint_as_float(a.z & 0xffff0000u), __uint_as_float(a.w << 16), __uint_as_float(a.w & 0xffff0000u)};
;     d[2] = (f32x4){__uint_as_float(c.x << 16), __uint_as_float(c.x & 0xffff0000u), __uint_as_float(c.y << 16), __uint_as_float(c.y & 0xffff0000u)};
;     d[3] = (f32x4){__uint_as_float(c.z << 16), __uint_as_float(c.z & 0xffff0000u), __uint_as_float(c.w << 16), __uint_as_float(c.w & 0xffff0000u)};
; }
; __device__ __forceinline__ void s5_step(const S5Lane& q, const float* urow, f32x2& x) {
;     const f32x4* u4 = (const f32x4*)urow;
;     f32x2 b0 = (f32x2){0.f, 0.f}, b1 = b0;
; #pragma unroll
;     for (int c4 = 0; c4 < 4; ++c4) { const f32x4 uv = u4[c4];
;         b0 += q.bb[c4 * 4 + 0] * uv[0]; b1 += q.bb[c4 * 4 + 1] * uv[1]; b0 += q.bb[c4 * 4 + 2] * uv[2]; b1 += q.bb[c4 * 4 + 3] * uv[3]; }
;     const f32x2 rot = (f32x2){-x.y, x.x};
;     x = (x * q.ar + rot * q.ai) + (b0 + b1);
; }
; __device__ __forceinline__ void s5_write_bbl(const S5Lane& q, bf16_t* bbL, int lane) {
;     u32x4 re0, re1, im0, im1;
;     re0.x = pk2(q.bb[0].x, q.bb[1].x); re0.y = pk2(q.bb[2].x, q.bb[3].x); re0.z = pk2(q.bb[4].x, q.bb[5].x); re0.w = pk2(q.bb[6].x, q.bb[7].x);
;     re1.x = pk2(q.bb[8].x, q.bb[9].x); re1.y = pk2(q.bb[10].x, q.bb[11].x); re1.z = pk2(q.bb[12].x, q.bb[13].x); re1.w = pk2(q.bb[14].x, q.bb[15].x);
	v_mov_b32_e32 v14, v130
	v_mov_b32_e32 v15, v131
	v_mov_b32_e32 v16, v132
	v_mov_b32_e32 v17, v133
	v_mov_b32_e32 v26, v134
	v_mov_b32_e32 v27, v135
	v_mov_b32_e32 v28, v136
	v_mov_b32_e32 v29, v137
	v_mov_b32_e32 v30, v138
	v_mov_b32_e32 v31, v139
	v_mov_b32_e32 v32, v140
	v_mov_b32_e32 v33, v141
	v_mov_b32_e32 v34, v142
	v_mov_b32_e32 v35, v143
	v_mov_b32_e32 v36, v144
	v_mov_b32_e32 v37, v145
	v_mov_b32_e32 v6, v146
	v_mov_b32_e32 v7, v147
	v_mov_b32_e32 v8, v148
	v_mov_b32_e32 v9, v149
	v_mov_b32_e32 v10, v150
	v_mov_b32_e32 v11, v151
	v_mov_b32_e32 v12, v152
	v_mov_b32_e32 v13, v153
	v_mov_b32_e32 v18, v154
	v_mov_b32_e32 v19, v155
	v_mov_b32_e32 v20, v156
	v_mov_b32_e32 v21, v157
	v_mov_b32_e32 v22, v158
	v_mov_b32_e32 v23, v159
	v_mov_b32_e32 v24, v160
	v_mov_b32_e32 v25, v161
	v_mov_b32_e32 v78, v162
	v_mov_b32_e32 v79, v163
	v_mov_b32_e32 v80, v164
	v_mov_b32_e32 v81, v165
	v_mov_b32_e32 v42, v166
	v_mov_b32_e32 v43, v167
	v_mov_b32_e32 v44, v168
	v_mov_b32_e32 v45, v169
	v_mov_b32_e32 v38, v170
	v_mov_b32_e32 v39, v171
	v_mov_b32_e32 v40, v172
	v_mov_b32_e32 v41, v173
	v_mov_b32_e32 v2, v174
	v_mov_b32_e32 v3, v175
	v_mov_b32_e32 v4, v176
	v_mov_b32_e32 v5, v177
	v_pk_mul_f32 v[90:91], v[22:23], v[88:89] op_sel_hi:[1,0]
	v_pk_mul_f32 v[96:97], v[24:25], v[88:89] op_sel_hi:[1,0]
	v_pk_fma_f32 v[90:91], v[34:35], v[86:87], v[90:91] op_sel_hi:[1,0,1] neg_lo:[0,0,1] neg_hi:[0,0,1]
	v_pk_mul_f32 v[34:35], v[34:35], v[88:89] op_sel_hi:[1,0]
	v_pk_mul_f32 v[102:103], v[18:19], v[88:89] op_sel_hi:[1,0]
	v_pk_mul_f32 v[104:105], v[20:21], v[88:89] op_sel_hi:[1,0]
	v_pk_mul_f32 v[106:107], v[10:11], v[88:89] op_sel_hi:[1,0]
	v_pk_mul_f32 v[108:109], v[12:13], v[88:89] op_sel_hi:[1,0]
	v_pk_mul_f32 v[110:111], v[6:7], v[88:89] op_sel_hi:[1,0]
	v_pk_mul_f32 v[112:113], v[8:9], v[88:89] op_sel_hi:[1,0]
	v_pk_fma_f32 v[96:97], v[36:37], v[86:87], v[96:97] op_sel_hi:[1,0,1] neg_lo:[0,0,1] neg_hi:[0,0,1]
	v_pk_mul_f32 v[36:37], v[36:37], v[88:89] op_sel_hi:[1,0]
	v_pk_fma_f32 v[102:103], v[30:31], v[86:87], v[102:103] op_sel_hi:[1,0,1] neg_lo:[0,0,1] neg_hi:[0,0,1]
	v_pk_mul_f32 v[30:31], v[30:31], v[88:89] op_sel_hi:[1,0]
	v_pk_fma_f32 v[104:105], v[32:33], v[86:87], v[104:105] op_sel_hi:[1,0,1] neg_lo:[0,0,1] neg_hi:[0,0,1]
	v_pk_mul_f32 v[32:33], v[32:33], v[88:89] op_sel_hi:[1,0]
	v_pk_fma_f32 v[106:107], v[26:27], v[86:87], v[106:107] op_sel_hi:[1,0,1] neg_lo:[0,0,1] neg_hi:[0,0,1]
	v_pk_mul_f32 v[26:27], v[26:27], v[88:89] op_sel_hi:[1,0]
	v_pk_fma_f32 v[108:109], v[28:29], v[86:87], v[108:109] op_sel_hi:[1,0,1] neg_lo:[0,0,1] neg_hi:[0,0,1]
	v_pk_mul_f32 v[28:29], v[28:29], v[88:89] op_sel_hi:[1,0]
	v_pk_fma_f32 v[110:111], v[14:15], v[86:87], v[110:111] op_sel_hi:[1,0,1] neg_lo:[0,0,1] neg_hi:[0,0,1]
	v_pk_mul_f32 v[14:15], v[14:15], v[88:89] op_sel_hi:[1,0]
	v_pk_fma_f32 v[112:113], v[16:17], v[86:87], v[112:113] op_sel_hi:[1,0,1] neg_lo:[0,0,1] neg_hi:[0,0,1]
	v_pk_mul_f32 v[16:17], v[16:17], v[88:89] op_sel_hi:[1,0]
	v_pk_fma_f32 v[22:23], v[22:23], v[86:87], v[34:35] op_sel_hi:[1,0,1]
	v_pk_fma_f32 v[24:25], v[24:25], v[86:87], v[36:37] op_sel_hi:[1,0,1]
	v_pk_fma_f32 v[18:19], v[18:19], v[86:87], v[30:31] op_sel_hi:[1,0,1]
	v_pk_fma_f32 v[20:21], v[20:21], v[86:87], v[32:33] op_sel_hi:[1,0,1]
	v_pk_fma_f32 v[26:27], v[10:11], v[86:87], v[26:27] op_sel_hi:[1,0,1]
	v_pk_fma_f32 v[28:29], v[12:13], v[86:87], v[28:29] op_sel_hi:[1,0,1]
	v_pk_fma_f32 v[30:31], v[6:7], v[86:87], v[14:15] op_sel_hi:[1,0,1]
	v_pk_fma_f32 v[32:33], v[8:9], v[86:87], v[16:17] op_sel_hi:[1,0,1]
	v_cvt_pk_bf16_f32 v6, v90, v91
	v_cvt_pk_bf16_f32 v7, v96, v97
	v_cvt_pk_bf16_f32 v8, v102, v103
	v_cvt_pk_bf16_f32 v9, v104, v105
	v_cvt_pk_bf16_f32 v14, v22, v23
	v_add_u32_e32 v22, 0, v99
	v_cmp_lt_i32_e32 vcc, 0, v94
	v_lshlrev_b32_e32 v90, 3, v98
	v_mov_b32_e32 v86, v87
	v_cvt_pk_bf16_f32 v10, v106, v107
	v_cvt_pk_bf16_f32 v11, v108, v109
	v_cvt_pk_bf16_f32 v12, v110, v111
	v_cvt_pk_bf16_f32 v13, v112, v113
	v_cvt_pk_bf16_f32 v15, v24, v25
	v_cvt_pk_bf16_f32 v16, v18, v19
	v_cvt_pk_bf16_f32 v17, v20, v21
	v_cvt_pk_bf16_f32 v18, v26, v27
	v_cvt_pk_bf16_f32 v19, v28, v29
	v_cvt_pk_bf16_f32 v20, v30, v31
	v_cvt_pk_bf16_f32 v21, v32, v33
	ds_write_b128 v22, v[6:9]
	ds_write_b128 v22, v[10:13] offset:16
	ds_write_b128 v22, v[14:17] offset:2048
	ds_write_b128 v22, v[18:21] offset:2064
	s_and_saveexec_b64 s[52:53], vcc
	s_cbranch_execz .LBB0_710
; __device__ __forceinline__ void s5_pass2_item(PP p, unsigned char* shm, int item, int l) {
;     ...
;     float pr = q.ar, pi = q.ai;
; #pragma unroll
;     for (int s = 0; s < 6; ++s) { const float nr = pr * pr - pi * pi, ni = 2.f * pr * pi; pr = nr; pi = ni; }
;     f32x2 x = (f32x2){0.f, 0.f};
;     const f32x2* carry = (const f32x2*)((const float*)(p->ws + WS_CARRY) + ((size_t)((b * 32 + g) * 32) * 64 + lane) * 2);
;     for (int i0 = 0; i0 < j; i0 += 8) {
;         f32x2 sv[8];
; #pragma unroll
;         for (int e = 0; e < 8; ++e) sv[e] = (i0 + e < j) ? carry[(size_t)(i0 + e) * 64] : (f32x2){0.f, 0.f};
; #pragma unroll
;         for (int e = 0; e < 8; ++e) if (i0 + e < j) { const f32x2 rot = (f32x2){-x.y, x.x}; x = (x * pr + rot * pi) + sv[e]; }
	v_mul_f32_e32 v6, v89, v89
	v_add_f32_e32 v7, v84, v84
	v_fma_f32 v6, v84, v84, -v6
	v_mul_f32_e32 v8, v89, v7
	v_mov_b32_e32 v233, v6
	v_pk_mul_f32 v[10:11], v[6:7], v[232:233] op_sel_hi:[0,1]
	v_mul_f32_e32 v9, v8, v8
	v_pk_mul_f32 v[10:11], v[10:11], v[8:9]
	v_pk_fma_f32 v[6:7], v[6:7], v[232:233], v[8:9] op_sel_hi:[0,1,1] neg_lo:[0,0,1] neg_hi:[0,0,1]
	v_mov_b32_e32 v11, v7
	v_mul_f32_e32 v6, v7, v7
	v_add_f32_e32 v9, v7, v7
	v_pk_fma_f32 v[6:7], v[10:11], v[10:11], v[6:7] op_sel_hi:[1,1,0] neg_lo:[1,0,0] neg_hi:[1,0,0]
	s_lshl_b32 s2, s40, 10
	v_mul_f32_e32 v7, v10, v9
	v_mul_f32_e32 v10, v6, v6
	v_pk_fma_f32 v[10:11], v[6:7], v[6:7], v[10:11] op_sel_hi:[1,1,0] neg_lo:[1,0,0] neg_hi:[1,0,0]
	s_lshl_b32 s3, s16, 5
	v_add_f32_e32 v8, v6, v6
	v_mov_b32_e32 v6, v7
	v_mov_b32_e32 v7, v11
	v_mov_b32_e32 v9, v11
	s_add_i32 s2, s3, s2
	v_pk_mul_f32 v[6:7], v[6:7], v[8:9]
	s_ashr_i32 s3, s2, 31
	v_pk_mov_b32 v[8:9], v[10:11], v[6:7] op_sel:[1,0]
	v_mov_b32_e32 v233, v6
	s_lshl_b64 s[2:3], s[2:3], 9
	v_pk_mul_f32 v[10:11], v[8:9], v[232:233]
	s_add_u32 s2, s28, s2
	v_pk_mul_f32 v[10:11], v[6:7], v[10:11]
	v_pk_fma_f32 v[6:7], v[8:9], v[232:233], v[6:7] neg_lo:[1,0,0] neg_hi:[1,0,0]
	v_mov_b32_e32 v91, v1
	v_mov_b32_e32 v11, v7
	v_add_f32_e32 v6, v7, v7
	s_addc_u32 s3, s29, s3
	v_mul_f32_e32 v6, v10, v6
	v_pk_mul_f32 v[8:9], v[10:11], v[10:11]
	v_lshl_add_u64 v[10:11], s[2:3], 0, v[90:91]
	s_mov_b64 s[2:3], 0x31ac0e00
	v_mov_b32_e32 v86, 0
	v_mov_b32_e32 v30, 0x3c0881c4
	v_pk_add_f32 v[8:9], v[8:9], v[8:9] op_sel:[1,0] op_sel_hi:[1,0] neg_lo:[0,1] neg_hi:[0,1]
	v_mov_b32_e32 v7, v6
	v_lshl_add_u64 v[10:11], v[10:11], 0, s[2:3]
	s_mov_b32 s20, 0
	s_mov_b64 s[2:3], 0
	v_mov_b32_e32 v87, v86
	v_readfirstlane_b32 s20, v94
	global_load_dwordx2 v[140:141], v[10:11], off offset:-3584
	global_load_dwordx2 v[142:143], v[10:11], off offset:-3072
	global_load_dwordx2 v[144:145], v[10:11], off offset:-2560
	global_load_dwordx2 v[146:147], v[10:11], off offset:-2048
	global_load_dwordx2 v[148:149], v[10:11], off offset:-1536
	global_load_dwordx2 v[150:151], v[10:11], off offset:-1024
	global_load_dwordx2 v[152:153], v[10:11], off offset:-512
	global_load_dwordx2 v[154:155], v[10:11], off
	s_cmp_le_u32 s20, 8
	s_cbranch_scc1 .Ls5c_ld_done
	s_mov_b64 s[16:17], 0x1000
	v_lshl_add_u64 v[130:131], v[10:11], 0, s[16:17]
	global_load_dwordx2 v[156:157], v[130:131], off offset:-3584
	global_load_dwordx2 v[158:159], v[130:131], off offset:-3072
	global_load_dwordx2 v[160:161], v[130:131], off offset:-2560
	global_load_dwordx2 v[162:163], v[130:131], off offset:-2048
	global_load_dwordx2 v[164:165], v[130:131], off offset:-1536
	global_load_dwordx2 v[166:167], v[130:131], off offset:-1024
	global_load_dwordx2 v[168:169], v[130:131], off offset:-512
	global_load_dwordx2 v[170:171], v[130:131], off
	s_cmp_le_u32 s20, 16
	s_cbranch_scc1 .Ls5c_ld_done
	s_mov_b64 s[16:17], 0x2000
	v_lshl_add_u64 v[132:133], v[10:11], 0, s[16:17]
	global_load_dwordx2 v[180:181], v[132:133], off offset:-3584
	global_load_dwordx2 v[182:183], v[132:133], off offset:-3072
	global_load_dwordx2 v[184:185], v[132:133], off offset:-2560
	global_load_dwordx2 v[186:187], v[132:133], off offset:-2048
	global_load_dwordx2 v[188:189], v[132:133], off offset:-1536
	global_load_dwordx2 v[190:191], v[132:133], off offset:-1024
	global_load_dwordx2 v[192:193], v[132:133], off offset:-512
	global_load_dwordx2 v[194:195], v[132:133], off
	s_cmp_le_u32 s20, 24
	s_cbranch_scc1 .Ls5c_ld_done
	s_mov_b64 s[16:17], 0x3000
	v_lshl_add_u64 v[134:135], v[10:11], 0, s[16:17]
	global_load_dwordx2 v[196:197], v[134:135], off offset:-3584
	global_load_dwordx2 v[198:199], v[134:135], off offset:-3072
	global_load_dwordx2 v[200:201], v[134:135], off offset:-2560
	global_load_dwordx2 v[202:203], v[134:135], off offset:-2048
	global_load_dwordx2 v[204:205], v[134:135], off offset:-1536
	global_load_dwordx2 v[206:207], v[134:135], off offset:-1024
	global_load_dwordx2 v[208:209], v[134:135], off offset:-512
	global_load_dwordx2 v[210:211], v[134:135], off
